# c4 + attention counted lgkmcnt waits (PV groups, QK read hoist) + RG-LRU segment scan with batched LDS reads
# speedup vs baseline: 1.0040x; 1.0018x over previous
; DEVI unsigned cvtpk(float lo, float hi) { unsigned r; asm volatile("v_cvt_pk_bf16_f32 %0, %1, %2" : "=v"(r) : "v"(lo), "v"(hi)); return r; }
; DEVI float bflo(unsigned w) { return __uint_as_float(w << 16); }
; DEVI float bfhi(unsigned w) { return __uint_as_float(w & 0xffff0000u); }
; #define RNN_LOAD(j_) do { const int b_ = (j_) >> 7, t0_ = ((j_) & 127) * 128; _Pragma("unroll") for (int k = 0; k < 4; ++k) { const int s_ = t0_ + tok - 3 + k; \
;         const bf16_t* p_ = xr + ((size_t)b_ * SEQ + (s_ < 0 ? 0 : s_)) * DM + ch0 + cg4; xw[2 * k] = *(const u32x4*)p_; xw[2 * k + 1] = *(const u32x4*)(p_ + 8); } } while (0)
; DEVI void rnn_local_phase(const bf16_t* xr, const float* convw, const float* convb, const bf16_t* lruT, const float* ba, const float* bx, const float* lam,
;                           bf16_t* hloc, bf16_t* pcum, float* aggA, float* aggH, char* lds, int wv) {
;     ...
;             float xc[16];
; #pragma unroll
;             for (int i = 0; i < 16; i += 4) { const f32x4 bb = *(const f32x4*)(cwL + 256 + cg4 + i); xc[i] = bb[0]; xc[i + 1] = bb[1]; xc[i + 2] = bb[2]; xc[i + 3] = bb[3]; }
; #pragma unroll
;             for (int k = 0; k < 4; ++k) { const float zf = (t0 + tok - 3 + k) >= 0 ? 1.f : 0.f; const u32x4 w0 = xw[2 * k], w1 = xw[2 * k + 1];
;                 const float xv[16] = {bflo(w0.x), bfhi(w0.x), bflo(w0.y), bfhi(w0.y), bflo(w0.z), bfhi(w0.z), bflo(w0.w), bfhi(w0.w), bflo(w1.x), bfhi(w1.x), bflo(w1.y), bfhi(w1.y), bflo(w1.z), bfhi(w1.z), bflo(w1.w), bfhi(w1.w)};
; #pragma unroll
;                 for (int i = 0; i < 16; i += 4) { const f32x4 cw = *(const f32x4*)(cwL + k * 64 + cg4 + i) * zf; xc[i] += cw[0] * xv[i]; xc[i + 1] += cw[1] * xv[i + 1]; xc[i + 2] += cw[2] * xv[i + 2]; xc[i + 3] += cw[3] * xv[i + 3]; } }
;             if (j + ns < 256) RNN_LOAD(j + ns);
; #pragma unroll
;             for (int i = 0; i < 16; ++i) xcf[tok * 65 + cg4 + i] = xc[i];
;             u32x4 o0 = {cvtpk(xc[0], xc[1]), cvtpk(xc[2], xc[3]), cvtpk(xc[4], xc[5]), cvtpk(xc[6], xc[7])}, o1 = {cvtpk(xc[8], xc[9]), cvtpk(xc[10], xc[11]), cvtpk(xc[12], xc[13]), cvtpk(xc[14], xc[15])};
;             *(u32x4*)(xcb + tok * 72 + cg4) = o0; *(u32x4*)(xcb + tok * 72 + cg4 + 8) = o1;
.LBB0_123:
	s_and_b32 s78, s60, 0x7f
	s_lshl_b32 s79, s78, 7
	v_add_u32_e32 v196, s79, v157
	v_cmp_lt_i32_e32 vcc, 2, v196
	v_and_b32_e32 v197, 0xffff0000, v62
	s_nop 0
	v_cndmask_b32_e64 v0, 0, 1.0, vcc
	v_cmp_lt_i32_e32 vcc, 1, v196
	s_waitcnt lgkmcnt(0)
	v_pk_mul_f32 v[144:145], v[144:145], v[0:1] op_sel_hi:[1,0]
	v_pk_mul_f32 v[142:143], v[142:143], v[0:1] op_sel_hi:[1,0]
	v_pk_mul_f32 v[140:141], v[140:141], v[0:1] op_sel_hi:[1,0]
	v_pk_mul_f32 v[138:139], v[138:139], v[0:1] op_sel_hi:[1,0]
	v_pk_mul_f32 v[136:137], v[0:1], v[136:137] op_sel_hi:[0,1]
	v_pk_mul_f32 v[134:135], v[0:1], v[134:135] op_sel_hi:[0,1]
	v_pk_mul_f32 v[132:133], v[0:1], v[132:133] op_sel_hi:[0,1]
	v_pk_mul_f32 v[130:131], v[0:1], v[130:131] op_sel_hi:[0,1]
	v_cndmask_b32_e64 v0, 0, 1.0, vcc
	v_cmp_lt_i32_e32 vcc, 0, v196
	v_pk_mul_f32 v[128:129], v[0:1], v[128:129] op_sel_hi:[0,1]
	v_pk_mul_f32 v[126:127], v[0:1], v[126:127] op_sel_hi:[0,1]
	v_pk_mul_f32 v[124:125], v[0:1], v[124:125] op_sel_hi:[0,1]
	v_pk_mul_f32 v[122:123], v[0:1], v[122:123] op_sel_hi:[0,1]
	v_pk_mul_f32 v[120:121], v[0:1], v[120:121] op_sel_hi:[0,1]
	v_pk_mul_f32 v[118:119], v[0:1], v[118:119] op_sel_hi:[0,1]
	v_pk_mul_f32 v[116:117], v[0:1], v[116:117] op_sel_hi:[0,1]
	v_pk_mul_f32 v[114:115], v[0:1], v[114:115] op_sel_hi:[0,1]
	v_cndmask_b32_e64 v0, 0, 1.0, vcc
	v_cmp_lt_i32_e32 vcc, -1, v196
	v_lshlrev_b32_e32 v196, 16, v62
	v_lshlrev_b32_e32 v62, 16, v63
	v_and_b32_e32 v63, 0xffff0000, v63
	v_pk_fma_f32 v[90:91], v[142:143], v[196:197], v[90:91]
	v_lshlrev_b32_e32 v142, 16, v58
	v_and_b32_e32 v143, 0xffff0000, v58
	v_pk_fma_f32 v[62:63], v[144:145], v[62:63], v[92:93]
	v_lshlrev_b32_e32 v58, 16, v59
	v_and_b32_e32 v59, 0xffff0000, v59
	v_pk_fma_f32 v[58:59], v[128:129], v[58:59], v[62:63]
	v_lshlrev_b32_e32 v62, 16, v64
	v_and_b32_e32 v63, 0xffff0000, v64
	v_pk_fma_f32 v[62:63], v[138:139], v[62:63], v[82:83]
	v_lshlrev_b32_e32 v82, 16, v60
	v_and_b32_e32 v83, 0xffff0000, v60
	v_pk_mul_f32 v[112:113], v[0:1], v[112:113] op_sel_hi:[0,1]
	v_pk_mul_f32 v[110:111], v[0:1], v[110:111] op_sel_hi:[0,1]
	v_pk_mul_f32 v[108:109], v[0:1], v[108:109] op_sel_hi:[0,1]
	v_pk_mul_f32 v[106:107], v[0:1], v[106:107] op_sel_hi:[0,1]
	v_pk_mul_f32 v[104:105], v[0:1], v[104:105] op_sel_hi:[0,1]
	v_pk_mul_f32 v[102:103], v[0:1], v[102:103] op_sel_hi:[0,1]
	v_pk_mul_f32 v[100:101], v[0:1], v[100:101] op_sel_hi:[0,1]
	v_pk_mul_f32 v[98:99], v[0:1], v[98:99] op_sel_hi:[0,1]
	v_cndmask_b32_e64 v0, 0, 1.0, vcc
	v_pk_fma_f32 v[90:91], v[126:127], v[142:143], v[90:91]
	v_lshlrev_b32_e32 v126, 16, v54
	v_and_b32_e32 v127, 0xffff0000, v54
	v_lshlrev_b32_e32 v54, 16, v55
	v_and_b32_e32 v55, 0xffff0000, v55
	v_pk_fma_f32 v[62:63], v[122:123], v[82:83], v[62:63]
	v_lshlrev_b32_e32 v82, 16, v56
	v_and_b32_e32 v83, 0xffff0000, v56
	v_pk_fma_f32 v[54:55], v[112:113], v[54:55], v[58:59]
	v_pk_mul_f32 v[58:59], v[0:1], v[86:87] op_sel_hi:[0,1]
	v_pk_fma_f32 v[62:63], v[106:107], v[82:83], v[62:63]
	v_lshlrev_b32_e32 v82, 16, v52
	v_and_b32_e32 v83, 0xffff0000, v52
	v_pk_fma_f32 v[58:59], v[58:59], v[82:83], v[62:63]
	v_lshlrev_b32_e32 v62, 16, v65
	v_and_b32_e32 v63, 0xffff0000, v65
	v_pk_fma_f32 v[62:63], v[140:141], v[62:63], v[84:85]
	v_lshlrev_b32_e32 v60, 16, v61
	v_and_b32_e32 v61, 0xffff0000, v61
	v_pk_fma_f32 v[60:61], v[124:125], v[60:61], v[62:63]
	v_lshlrev_b32_e32 v56, 16, v57
	v_and_b32_e32 v57, 0xffff0000, v57
	v_pk_fma_f32 v[56:57], v[108:109], v[56:57], v[60:61]
	v_lshlrev_b32_e32 v60, 16, v46
	v_and_b32_e32 v61, 0xffff0000, v46
	v_lshlrev_b32_e32 v46, 16, v47
	v_and_b32_e32 v47, 0xffff0000, v47
	v_pk_mul_f32 v[96:97], v[0:1], v[96:97] op_sel_hi:[0,1]
	v_pk_fma_f32 v[90:91], v[110:111], v[126:127], v[90:91]
	v_lshlrev_b32_e32 v110, 16, v50
	v_and_b32_e32 v111, 0xffff0000, v50
	v_lshlrev_b32_e32 v50, 16, v51
	v_and_b32_e32 v51, 0xffff0000, v51
	v_pk_fma_f32 v[60:61], v[134:135], v[60:61], v[74:75]
	v_lshlrev_b32_e32 v62, 16, v42
	v_and_b32_e32 v63, 0xffff0000, v42
	v_pk_fma_f32 v[46:47], v[136:137], v[46:47], v[76:77]
	v_lshlrev_b32_e32 v42, 16, v43
	v_and_b32_e32 v43, 0xffff0000, v43
	v_pk_fma_f32 v[50:51], v[96:97], v[50:51], v[54:55]
	v_pk_mul_f32 v[54:55], v[0:1], v[88:89] op_sel_hi:[0,1]
	v_lshlrev_b32_e32 v52, 16, v53
	v_and_b32_e32 v53, 0xffff0000, v53
	v_pk_fma_f32 v[60:61], v[118:119], v[62:63], v[60:61]
	v_lshlrev_b32_e32 v62, 16, v38
	v_and_b32_e32 v63, 0xffff0000, v38
	v_pk_fma_f32 v[42:43], v[120:121], v[42:43], v[46:47]
	v_lshlrev_b32_e32 v38, 16, v39
	v_and_b32_e32 v39, 0xffff0000, v39
	v_pk_mul_f32 v[94:95], v[0:1], v[94:95] op_sel_hi:[0,1]
	v_pk_fma_f32 v[52:53], v[54:55], v[52:53], v[56:57]
	v_pk_mul_f32 v[54:55], v[0:1], v[80:81] op_sel_hi:[0,1]
	v_pk_fma_f32 v[60:61], v[102:103], v[62:63], v[60:61]
	v_lshlrev_b32_e32 v62, 16, v34
	v_and_b32_e32 v63, 0xffff0000, v34
	v_pk_fma_f32 v[38:39], v[104:105], v[38:39], v[42:43]
	v_lshlrev_b32_e32 v34, 16, v35
	v_and_b32_e32 v35, 0xffff0000, v35
	v_lshlrev_b32_e32 v46, 16, v48
	v_and_b32_e32 v47, 0xffff0000, v48
	v_pk_fma_f32 v[90:91], v[94:95], v[110:111], v[90:91]
	v_pk_mul_f32 v[56:57], v[0:1], v[78:79] op_sel_hi:[0,1]
	v_pk_fma_f32 v[42:43], v[54:55], v[34:35], v[38:39]
	v_pk_mul_f32 v[34:35], v[0:1], v[72:73] op_sel_hi:[0,1]
	v_pk_mul_f32 v[38:39], v[0:1], v[70:71] op_sel_hi:[0,1]
	v_pk_fma_f32 v[46:47], v[130:131], v[46:47], v[66:67]
	v_lshlrev_b32_e32 v54, 16, v44
	v_and_b32_e32 v55, 0xffff0000, v44
	v_add_u32_e32 v0, 0x4800, v220
	v_pk_fma_f32 v[46:47], v[114:115], v[54:55], v[46:47]
	v_lshlrev_b32_e32 v54, 16, v40
	v_and_b32_e32 v55, 0xffff0000, v40
	ds_write2_b32 v0, v90, v91 offset1:1
	v_add_u32_e32 v0, 0x4808, v220
; DEVI float bflo(unsigned w) { return __uint_as_float(w << 16); }
; DEVI void rnn_local_phase(const bf16_t* xr, const float* convw, const float* convb, const bf16_t* lruT, const float* ba, const float* bx, const float* lam,
;                           bf16_t* hloc, bf16_t* pcum, float* aggA, float* aggH, char* lds, int wv) {
;     ...
;             for (int k = 0; k < 4; ++k) { const float zf = (t0 + tok - 3 + k) >= 0 ? 1.f : 0.f; const u32x4 w0 = xw[2 * k], w1 = xw[2 * k + 1];
;                 const float xv[16] = {bflo(w0.x), bfhi(w0.x), bflo(w0.y), bfhi(w0.y), bflo(w0.z), bfhi(w0.z), bflo(w0.w), bfhi(w0.w), bflo(w1.x), bfhi(w1.x), bflo(w1.y), bfhi(w1.y), bflo(w1.z), bfhi(w1.z), bflo(w1.w), bfhi(w1.w)};
; #pragma unroll
;                 for (int i = 0; i < 16; i += 4) { const f32x4 cw = *(const f32x4*)(cwL + k * 64 + cg4 + i) * zf; xc[i] += cw[0] * xv[i]; xc[i + 1] += cw[1] * xv[i + 1]; xc[i + 2] += cw[2] * xv[i + 2]; xc[i + 3] += cw[3] * xv[i + 3]; } }
;             if (j + ns < 256) RNN_LOAD(j + ns);
; #pragma unroll
;             for (int i = 0; i < 16; ++i) xcf[tok * 65 + cg4 + i] = xc[i];
;             u32x4 o0 = {cvtpk(xc[0], xc[1]), cvtpk(xc[2], xc[3]), cvtpk(xc[4], xc[5]), cvtpk(xc[6], xc[7])}, o1 = {cvtpk(xc[8], xc[9]), cvtpk(xc[10], xc[11]), cvtpk(xc[12], xc[13]), cvtpk(xc[14], xc[15])};
;             *(u32x4*)(xcb + tok * 72 + cg4) = o0; *(u32x4*)(xcb + tok * 72 + cg4 + 8) = o1;
;         }
;         LBAR();
;         {
;             const bf16x8 a0 = *(const bf16x8*)(xcb + (wave * 16 + l16) * 72 + q4 * 8), a1 = *(const bf16x8*)(xcb + (wave * 16 + l16) * 72 + 32 + q4 * 8);
; #pragma unroll
;             for (int cg = 0; cg < 4; ++cg) { const int ch = cg * 16 + l16;
;                 f32x4 ca = {0.f, 0.f, 0.f, 0.f}, cx = {0.f, 0.f, 0.f, 0.f};
;                 const bf16x8 wa0 = *(const bf16x8*)(WtL + ch * 72 + q4 * 8), wa1 = *(const bf16x8*)(WtL + ch * 72 + 32 + q4 * 8);
;                 const bf16x8 wx0 = *(const bf16x8*)(WtL + (64 + ch) * 72 + q4 * 8), wx1 = *(const bf16x8*)(WtL + (64 + ch) * 72 + 32 + q4 * 8);
;                 ca = __builtin_amdgcn_mfma_f32_16x16x32_bf16(a0, wa0, ca, 0, 0, 0); ca = __builtin_amdgcn_mfma_f32_16x16x32_bf16(a1, wa1, ca, 0, 0, 0);
;                 cx = __builtin_amdgcn_mfma_f32_16x16x32_bf16(a0, wx0, cx, 0, 0, 0); cx = __builtin_amdgcn_mfma_f32_16x16x32_bf16(a1, wx1, cx, 0, 0, 0);
; #pragma unroll
	v_pk_fma_f32 v[46:47], v[98:99], v[54:55], v[46:47]
	v_lshlrev_b32_e32 v54, 16, v36
	v_and_b32_e32 v55, 0xffff0000, v36
	ds_write2_b32 v0, v50, v51 offset1:1
	v_add_u32_e32 v0, 0x4810, v220
	v_pk_fma_f32 v[46:47], v[38:39], v[54:55], v[46:47]
	v_lshlrev_b32_e32 v38, 16, v49
	v_and_b32_e32 v39, 0xffff0000, v49
	ds_write2_b32 v0, v58, v59 offset1:1
	v_add_u32_e32 v0, 0x4818, v220
	v_pk_fma_f32 v[56:57], v[56:57], v[62:63], v[60:61]
	v_pk_fma_f32 v[38:39], v[132:133], v[38:39], v[68:69]
	v_lshlrev_b32_e32 v44, 16, v45
	v_and_b32_e32 v45, 0xffff0000, v45
	ds_write2_b32 v0, v52, v53 offset1:1
	v_add_u32_e32 v0, 0x4820, v220
	v_pk_fma_f32 v[38:39], v[116:117], v[44:45], v[38:39]
	v_lshlrev_b32_e32 v40, 16, v41
	v_and_b32_e32 v41, 0xffff0000, v41
	ds_write2_b32 v0, v56, v57 offset1:1
	v_add_u32_e32 v0, 0x4828, v220
	v_pk_fma_f32 v[38:39], v[100:101], v[40:41], v[38:39]
	v_lshlrev_b32_e32 v36, 16, v37
	v_and_b32_e32 v37, 0xffff0000, v37
	ds_write2_b32 v0, v42, v43 offset1:1
	v_add_u32_e32 v0, 0x4830, v220
	v_pk_fma_f32 v[44:45], v[34:35], v[36:37], v[38:39]
	ds_write2_b32 v0, v46, v47 offset1:1
	v_add_u32_e32 v0, 0x4838, v220
	ds_write2_b32 v0, v44, v45 offset1:1
	v_cvt_pk_bf16_f32 v34, v90, v91
	v_cvt_pk_bf16_f32 v35, v50, v51
	v_cvt_pk_bf16_f32 v36, v58, v59
	v_cvt_pk_bf16_f32 v37, v52, v53
	v_cvt_pk_bf16_f32 v38, v56, v57
	v_cvt_pk_bf16_f32 v39, v42, v43
	v_cvt_pk_bf16_f32 v40, v46, v47
	v_cvt_pk_bf16_f32 v41, v44, v45
	ds_write_b128 v221, v[34:37]
	ds_write_b128 v221, v[38:41] offset:16
	s_waitcnt lgkmcnt(0)
	s_barrier
	ds_read_b128 v[38:41], v165
	ds_read_b128 v[34:37], v165 offset:64
	ds_read_b128 v[42:45], v168
	ds_read_b128 v[46:49], v168 offset:64
	s_waitcnt lgkmcnt(0)
	v_mfma_f32_16x16x32_bf16 v[42:45], v[38:41], v[42:45], 0
	ds_read_b128 v[50:53], v168 offset:9216
	v_mfma_f32_16x16x32_bf16 v[46:49], v[34:37], v[46:49], v[42:45]
	s_nop 5
	ds_read_b128 v[42:45], v168 offset:9280
	s_waitcnt lgkmcnt(0)
	v_mfma_f32_16x16x32_bf16 v[50:53], v[38:41], v[50:53], 0
	v_add_f32_e32 v0, v149, v46
	v_mul_f32_e32 v0, 0xbfb8aa3b, v0
	v_exp_f32_e32 v0, v0
	v_mfma_f32_16x16x32_bf16 v[42:45], v[34:37], v[42:45], v[50:53]
	v_add_f32_e32 v0, 1.0, v0
	v_rcp_f32_e64 v46, -v0
	ds_read_b32 v0, v169 offset:18432
	v_mul_f32_e32 v46, v158, v46
	v_add_f32_e32 v51, v46, v46
	v_cmp_ngt_f32_e32 vcc, s40, v51
	s_and_saveexec_b64 s[10:11], vcc
	s_xor_b64 s[10:11], exec, s[10:11]
	v_mov_b32_e32 v50, 0x3e2aaaab
	v_fmamk_f32 v50, v51, 0x3d2aaaab, v50
	v_fma_f32 v50, v51, v50, 0.5
	v_fma_f32 v50, v51, v50, 1.0
	v_mul_f32_e64 v50, v50, -v51
	s_or_saveexec_b64 s[10:11], s[10:11]
	v_mul_f32_e32 v46, 0x3fb8aa3b, v46
	v_exp_f32_e32 v46, v46
	s_xor_b64 exec, exec, s[10:11]
	v_fma_f32 v50, -v46, v46, 1.0
	s_or_b64 exec, exec, s[10:11]
	v_add_f32_e32 v42, v152, v42
	v_mul_f32_e32 v42, 0xbfb8aa3b, v42
	v_exp_f32_e32 v42, v42
	v_max_f32_e32 v50, v50, v50
	v_add_f32_e32 v47, v149, v47
	v_max_f32_e32 v50, 0, v50
	v_add_f32_e32 v42, 1.0, v42
	v_rcp_f32_e32 v42, v42
	v_mul_f32_e32 v47, 0xbfb8aa3b, v47
	v_sqrt_f32_e32 v50, v50
	v_exp_f32_e32 v47, v47
	s_waitcnt lgkmcnt(0)
	v_mul_f32_e32 v0, v0, v42
	ds_write_b32 v169, v46 offset:51712
	v_mul_f32_e32 v42, v0, v50
	v_add_f32_e32 v0, 1.0, v47
	v_rcp_f32_e64 v47, -v0
	ds_read_b32 v0, v169 offset:18692
	ds_write_b32 v170, v42
	v_mul_f32_e32 v42, v158, v47
	v_add_f32_e32 v47, v42, v42
	v_cmp_ngt_f32_e32 vcc, s40, v47
	s_and_saveexec_b64 s[10:11], vcc
	s_xor_b64 s[10:11], exec, s[10:11]
	v_mov_b32_e32 v46, 0x3e2aaaab
	v_fmamk_f32 v46, v47, 0x3d2aaaab, v46
	v_fma_f32 v46, v47, v46, 0.5
	v_fma_f32 v46, v47, v46, 1.0
	v_mul_f32_e64 v46, v46, -v47
	s_or_saveexec_b64 s[10:11], s[10:11]
	v_mul_f32_e32 v42, 0x3fb8aa3b, v42
	v_exp_f32_e32 v42, v42
	s_xor_b64 exec, exec, s[10:11]
	v_fma_f32 v46, -v42, v42, 1.0
	s_or_b64 exec, exec, s[10:11]
	v_add_f32_e32 v43, v152, v43
	v_mul_f32_e32 v43, 0xbfb8aa3b, v43
	v_exp_f32_e32 v43, v43
	v_add_f32_e32 v47, v149, v48
	v_max_f32_e32 v46, v46, v46
	v_mul_f32_e32 v47, 0xbfb8aa3b, v47
	v_add_f32_e32 v43, 1.0, v43
	v_max_f32_e32 v46, 0, v46
	v_rcp_f32_e32 v43, v43
	v_exp_f32_e32 v47, v47
	v_sqrt_f32_e32 v46, v46
	ds_write_b32 v169, v42 offset:51972
	s_waitcnt lgkmcnt(0)
	v_mul_f32_e32 v0, v43, v0
	v_add_f32_e32 v42, 1.0, v47
	v_mul_f32_e32 v0, v0, v46
	v_rcp_f32_e64 v42, -v42
	ds_write_b32 v171, v0
	ds_read_b32 v0, v169 offset:18952
	v_mul_f32_e32 v42, v158, v42
	v_add_f32_e32 v46, v42, v42
	v_cmp_ngt_f32_e32 vcc, s40, v46
	s_and_saveexec_b64 s[10:11], vcc
	s_xor_b64 s[10:11], exec, s[10:11]
	v_mov_b32_e32 v43, 0x3e2aaaab
	v_fmamk_f32 v43, v46, 0x3d2aaaab, v43
	v_fma_f32 v43, v46, v43, 0.5
	v_fma_f32 v43, v46, v43, 1.0
	v_mul_f32_e64 v43, v43, -v46
	s_or_saveexec_b64 s[10:11], s[10:11]
	v_mul_f32_e32 v42, 0x3fb8aa3b, v42
	v_exp_f32_e32 v42, v42
	s_xor_b64 exec, exec, s[10:11]
	v_fma_f32 v43, -v42, v42, 1.0
	s_or_b64 exec, exec, s[10:11]
	v_add_f32_e32 v44, v152, v44
	v_mul_f32_e32 v44, 0xbfb8aa3b, v44
	v_exp_f32_e32 v44, v44
	v_add_f32_e32 v46, v149, v49
	v_max_f32_e32 v43, v43, v43
	v_mul_f32_e32 v46, 0xbfb8aa3b, v46
	v_add_f32_e32 v44, 1.0, v44
	v_max_f32_e32 v43, 0, v43
	v_rcp_f32_e32 v44, v44
	v_exp_f32_e32 v46, v46
	v_sqrt_f32_e32 v43, v43
	ds_write_b32 v169, v42 offset:52232
	s_waitcnt lgkmcnt(0)
; DEVI float sigmoidf_(float x) { return __builtin_amdgcn_rcpf(1.f + __expf(-x)); }
; DEVI void rnn_local_phase(const bf16_t* xr, const float* convw, const float* convb, const bf16_t* lruT, const float* ba, const float* bx, const float* lam,
;                           bf16_t* hloc, bf16_t* pcum, float* aggA, float* aggH, char* lds, int wv) {
;     ...
;             for (int cg = 0; cg < 4; ++cg) { const int ch = cg * 16 + l16;
;                 f32x4 ca = {0.f, 0.f, 0.f, 0.f}, cx = {0.f, 0.f, 0.f, 0.f};
;                 const bf16x8 wa0 = *(const bf16x8*)(WtL + ch * 72 + q4 * 8), wa1 = *(const bf16x8*)(WtL + ch * 72 + 32 + q4 * 8);
;                 const bf16x8 wx0 = *(const bf16x8*)(WtL + (64 + ch) * 72 + q4 * 8), wx1 = *(const bf16x8*)(WtL + (64 + ch) * 72 + 32 + q4 * 8);
;                 ca = __builtin_amdgcn_mfma_f32_16x16x32_bf16(a0, wa0, ca, 0, 0, 0); ca = __builtin_amdgcn_mfma_f32_16x16x32_bf16(a1, wa1, ca, 0, 0, 0);
;                 cx = __builtin_amdgcn_mfma_f32_16x16x32_bf16(a0, wx0, cx, 0, 0, 0); cx = __builtin_amdgcn_mfma_f32_16x16x32_bf16(a1, wx1, cx, 0, 0, 0);
; #pragma unroll
;                 for (int i = 0; i < 4; ++i) { const int tk = wave * 16 + q4 * 4 + i; const float xv = xcf[tk * 65 + ch];
;                     const float r = sigmoidf_(ca[i] + bav[cg]), ig = sigmoidf_(cx[i] + bxv[cg]), la = -r * sp8[cg], a = __expf(la);
;                     const float y2 = 2.f * la; const float om = y2 < -0.05f ? 1.f - a * a : -y2 * (1.f + y2 * (0.5f + y2 * (0.16666667f + y2 * 0.041666668f)));
;                     const float u = __builtin_amdgcn_sqrtf(fmaxf(om, 0.f)) * (ig * xv);
;                     aL[tk * 65 + ch] = a; uL[tk * 65 + ch] = u; } }
	v_mul_f32_e32 v0, v44, v0
	v_add_f32_e32 v42, 1.0, v46
	v_mul_f32_e32 v0, v0, v43
	v_rcp_f32_e64 v42, -v42
	ds_write_b32 v172, v0
	ds_read_b32 v0, v169 offset:19212
	v_mul_f32_e32 v43, v158, v42
	v_add_f32_e32 v44, v43, v43
	v_cmp_ngt_f32_e32 vcc, s40, v44
	s_and_saveexec_b64 s[10:11], vcc
	s_xor_b64 s[10:11], exec, s[10:11]
	v_mov_b32_e32 v42, 0x3e2aaaab
	v_fmamk_f32 v42, v44, 0x3d2aaaab, v42
	v_fma_f32 v42, v44, v42, 0.5
	v_fma_f32 v42, v44, v42, 1.0
	v_mul_f32_e64 v42, v42, -v44
	s_or_saveexec_b64 s[10:11], s[10:11]
	v_mul_f32_e32 v43, 0x3fb8aa3b, v43
	v_exp_f32_e32 v43, v43
	s_xor_b64 exec, exec, s[10:11]
	v_fma_f32 v42, -v43, v43, 1.0
	s_or_b64 exec, exec, s[10:11]
	v_add_f32_e32 v44, v152, v45
	v_mul_f32_e32 v44, 0xbfb8aa3b, v44
	v_exp_f32_e32 v44, v44
	v_max_f32_e32 v42, v42, v42
	v_max_f32_e32 v42, 0, v42
	v_sqrt_f32_e32 v42, v42
	v_add_f32_e32 v44, 1.0, v44
	v_rcp_f32_e32 v44, v44
	ds_write_b32 v169, v43 offset:52492
	s_waitcnt lgkmcnt(0)
	v_mul_f32_e32 v0, v44, v0
	v_mul_f32_e32 v0, v0, v42
	ds_write_b32 v173, v0
	ds_read_b128 v[42:45], v174
	ds_read_b32 v0, v169 offset:18496
	ds_read_b128 v[46:49], v174 offset:64
	ds_read_b128 v[50:53], v174 offset:9216
	s_waitcnt lgkmcnt(0)
	v_mfma_f32_16x16x32_bf16 v[42:45], v[38:41], v[42:45], 0
	v_mfma_f32_16x16x32_bf16 v[46:49], v[34:37], v[46:49], v[42:45]
	v_mfma_f32_16x16x32_bf16 v[50:53], v[38:41], v[50:53], 0
	s_nop 6
	v_add_f32_e32 v42, v150, v46
	v_mul_f32_e32 v42, 0xbfb8aa3b, v42
	v_exp_f32_e32 v46, v42
	ds_read_b128 v[42:45], v174 offset:9280
	s_waitcnt lgkmcnt(0)
	v_mfma_f32_16x16x32_bf16 v[42:45], v[34:37], v[42:45], v[50:53]
	v_add_f32_e32 v46, 1.0, v46
	v_rcp_f32_e64 v46, -v46
	s_nop 0
	v_mul_f32_e32 v46, v159, v46
	v_add_f32_e32 v51, v46, v46
	v_cmp_ngt_f32_e32 vcc, s40, v51
	s_and_saveexec_b64 s[10:11], vcc
	s_xor_b64 s[10:11], exec, s[10:11]
	v_mov_b32_e32 v50, 0x3e2aaaab
	v_fmamk_f32 v50, v51, 0x3d2aaaab, v50
	v_fma_f32 v50, v51, v50, 0.5
	v_fma_f32 v50, v51, v50, 1.0
	v_mul_f32_e64 v50, v50, -v51
	s_or_saveexec_b64 s[10:11], s[10:11]
	v_mul_f32_e32 v46, 0x3fb8aa3b, v46
	v_exp_f32_e32 v46, v46
	s_xor_b64 exec, exec, s[10:11]
	v_fma_f32 v50, -v46, v46, 1.0
	s_or_b64 exec, exec, s[10:11]
	v_add_f32_e32 v42, v153, v42
	v_mul_f32_e32 v42, 0xbfb8aa3b, v42
	v_exp_f32_e32 v42, v42
	v_max_f32_e32 v50, v50, v50
	v_add_f32_e32 v47, v150, v47
	v_max_f32_e32 v50, 0, v50
	v_add_f32_e32 v42, 1.0, v42
	v_rcp_f32_e32 v42, v42
	v_mul_f32_e32 v47, 0xbfb8aa3b, v47
	v_sqrt_f32_e32 v50, v50
	v_exp_f32_e32 v47, v47
	v_mul_f32_e32 v0, v0, v42
	ds_write_b32 v169, v46 offset:51776
	v_mul_f32_e32 v42, v0, v50
	v_add_f32_e32 v0, 1.0, v47
	v_rcp_f32_e64 v47, -v0
	ds_read_b32 v0, v176 offset:18692
	ds_write_b32 v175, v42
	v_mul_f32_e32 v42, v159, v47
	v_add_f32_e32 v47, v42, v42
	v_cmp_ngt_f32_e32 vcc, s40, v47
	s_and_saveexec_b64 s[10:11], vcc
	s_xor_b64 s[10:11], exec, s[10:11]
	v_mov_b32_e32 v46, 0x3e2aaaab
	v_fmamk_f32 v46, v47, 0x3d2aaaab, v46
	v_fma_f32 v46, v47, v46, 0.5
	v_fma_f32 v46, v47, v46, 1.0
	v_mul_f32_e64 v46, v46, -v47
	s_or_saveexec_b64 s[10:11], s[10:11]
	v_mul_f32_e32 v42, 0x3fb8aa3b, v42
	v_exp_f32_e32 v42, v42
	s_xor_b64 exec, exec, s[10:11]
	v_fma_f32 v46, -v42, v42, 1.0
	s_or_b64 exec, exec, s[10:11]
	v_add_f32_e32 v43, v153, v43
	v_mul_f32_e32 v43, 0xbfb8aa3b, v43
	v_exp_f32_e32 v43, v43
	v_add_f32_e32 v47, v150, v48
	v_max_f32_e32 v46, v46, v46
	v_mul_f32_e32 v47, 0xbfb8aa3b, v47
	v_add_f32_e32 v43, 1.0, v43
	v_max_f32_e32 v46, 0, v46
	v_rcp_f32_e32 v43, v43
	v_exp_f32_e32 v47, v47
	v_sqrt_f32_e32 v46, v46
	ds_write_b32 v176, v42 offset:51972
	s_waitcnt lgkmcnt(0)
	v_mul_f32_e32 v0, v43, v0
	v_add_f32_e32 v42, 1.0, v47
	v_mul_f32_e32 v0, v0, v46
	v_rcp_f32_e64 v42, -v42
	ds_write_b32 v177, v0
	ds_read_b32 v0, v176 offset:18952
	v_mul_f32_e32 v42, v159, v42
	v_add_f32_e32 v46, v42, v42
	v_cmp_ngt_f32_e32 vcc, s40, v46
	s_and_saveexec_b64 s[10:11], vcc
	s_xor_b64 s[10:11], exec, s[10:11]
	v_mov_b32_e32 v43, 0x3e2aaaab
	v_fmamk_f32 v43, v46, 0x3d2aaaab, v43
	v_fma_f32 v43, v46, v43, 0.5
	v_fma_f32 v43, v46, v43, 1.0
	v_mul_f32_e64 v43, v43, -v46
	s_or_saveexec_b64 s[10:11], s[10:11]
	v_mul_f32_e32 v42, 0x3fb8aa3b, v42
	v_exp_f32_e32 v42, v42
	s_xor_b64 exec, exec, s[10:11]
	v_fma_f32 v43, -v42, v42, 1.0
	s_or_b64 exec, exec, s[10:11]
	v_add_f32_e32 v44, v153, v44
	v_mul_f32_e32 v44, 0xbfb8aa3b, v44
	v_exp_f32_e32 v44, v44
	v_add_f32_e32 v46, v150, v49
	v_max_f32_e32 v43, v43, v43
	v_mul_f32_e32 v46, 0xbfb8aa3b, v46
	v_add_f32_e32 v44, 1.0, v44
	v_max_f32_e32 v43, 0, v43
	v_rcp_f32_e32 v44, v44
	v_exp_f32_e32 v46, v46
	v_sqrt_f32_e32 v43, v43
	ds_write_b32 v176, v42 offset:52232
	s_waitcnt lgkmcnt(0)
	v_mul_f32_e32 v0, v44, v0
	v_add_f32_e32 v42, 1.0, v46
	v_mul_f32_e32 v0, v0, v43
	v_rcp_f32_e64 v42, -v42
	ds_write_b32 v178, v0
	ds_read_b32 v0, v176 offset:19212
	v_mul_f32_e32 v43, v159, v42
	v_add_f32_e32 v44, v43, v43
	v_cmp_ngt_f32_e32 vcc, s40, v44
	s_and_saveexec_b64 s[10:11], vcc
	s_xor_b64 s[10:11], exec, s[10:11]
	v_mov_b32_e32 v42, 0x3e2aaaab
	v_fmamk_f32 v42, v44, 0x3d2aaaab, v42
	v_fma_f32 v42, v44, v42, 0.5
	v_fma_f32 v42, v44, v42, 1.0
	v_mul_f32_e64 v42, v42, -v44
	s_or_saveexec_b64 s[10:11], s[10:11]
	v_mul_f32_e32 v43, 0x3fb8aa3b, v43
	v_exp_f32_e32 v43, v43
	s_xor_b64 exec, exec, s[10:11]
	v_fma_f32 v42, -v43, v43, 1.0
	s_or_b64 exec, exec, s[10:11]
	v_add_f32_e32 v44, v153, v45
	v_mul_f32_e32 v44, 0xbfb8aa3b, v44
	v_exp_f32_e32 v44, v44
	v_max_f32_e32 v42, v42, v42
	v_max_f32_e32 v42, 0, v42
	v_sqrt_f32_e32 v42, v42
	v_add_f32_e32 v44, 1.0, v44
	v_rcp_f32_e32 v44, v44
	ds_write_b32 v176, v43 offset:52492
	s_waitcnt lgkmcnt(0)
; DEVI float sigmoidf_(float x) { return __builtin_amdgcn_rcpf(1.f + __expf(-x)); }
; DEVI void rnn_local_phase(const bf16_t* xr, const float* convw, const float* convb, const bf16_t* lruT, const float* ba, const float* bx, const float* lam,
;                           bf16_t* hloc, bf16_t* pcum, float* aggA, float* aggH, char* lds, int wv) {
;     ...
;             for (int cg = 0; cg < 4; ++cg) { const int ch = cg * 16 + l16;
;                 f32x4 ca = {0.f, 0.f, 0.f, 0.f}, cx = {0.f, 0.f, 0.f, 0.f};
;                 const bf16x8 wa0 = *(const bf16x8*)(WtL + ch * 72 + q4 * 8), wa1 = *(const bf16x8*)(WtL + ch * 72 + 32 + q4 * 8);
;                 const bf16x8 wx0 = *(const bf16x8*)(WtL + (64 + ch) * 72 + q4 * 8), wx1 = *(const bf16x8*)(WtL + (64 + ch) * 72 + 32 + q4 * 8);
;                 ca = __builtin_amdgcn_mfma_f32_16x16x32_bf16(a0, wa0, ca, 0, 0, 0); ca = __builtin_amdgcn_mfma_f32_16x16x32_bf16(a1, wa1, ca, 0, 0, 0);
;                 cx = __builtin_amdgcn_mfma_f32_16x16x32_bf16(a0, wx0, cx, 0, 0, 0); cx = __builtin_amdgcn_mfma_f32_16x16x32_bf16(a1, wx1, cx, 0, 0, 0);
; #pragma unroll
;                 for (int i = 0; i < 4; ++i) { const int tk = wave * 16 + q4 * 4 + i; const float xv = xcf[tk * 65 + ch];
;                     const float r = sigmoidf_(ca[i] + bav[cg]), ig = sigmoidf_(cx[i] + bxv[cg]), la = -r * sp8[cg], a = __expf(la);
;                     const float y2 = 2.f * la; const float om = y2 < -0.05f ? 1.f - a * a : -y2 * (1.f + y2 * (0.5f + y2 * (0.16666667f + y2 * 0.041666668f)));
;                     const float u = __builtin_amdgcn_sqrtf(fmaxf(om, 0.f)) * (ig * xv);
;                     aL[tk * 65 + ch] = a; uL[tk * 65 + ch] = u; } }
	v_mul_f32_e32 v0, v44, v0
	v_mul_f32_e32 v0, v0, v42
	ds_write_b32 v179, v0
	ds_read_b128 v[42:45], v180
	ds_read_b32 v0, v169 offset:18560
	ds_read_b128 v[46:49], v180 offset:64
	ds_read_b128 v[50:53], v180 offset:9216
	s_waitcnt lgkmcnt(0)
	v_mfma_f32_16x16x32_bf16 v[42:45], v[38:41], v[42:45], 0
	v_mfma_f32_16x16x32_bf16 v[46:49], v[34:37], v[46:49], v[42:45]
	v_mfma_f32_16x16x32_bf16 v[50:53], v[38:41], v[50:53], 0
	s_nop 6
	v_add_f32_e32 v42, v151, v46
	v_mul_f32_e32 v42, 0xbfb8aa3b, v42
	v_exp_f32_e32 v46, v42
	ds_read_b128 v[42:45], v180 offset:9280
	s_waitcnt lgkmcnt(0)
	v_mfma_f32_16x16x32_bf16 v[42:45], v[34:37], v[42:45], v[50:53]
	v_add_f32_e32 v46, 1.0, v46
	v_rcp_f32_e64 v46, -v46
	s_nop 0
	v_mul_f32_e32 v46, v160, v46
	v_add_f32_e32 v51, v46, v46
	v_cmp_ngt_f32_e32 vcc, s40, v51
	s_and_saveexec_b64 s[10:11], vcc
	s_xor_b64 s[10:11], exec, s[10:11]
	v_mov_b32_e32 v50, 0x3e2aaaab
	v_fmamk_f32 v50, v51, 0x3d2aaaab, v50
	v_fma_f32 v50, v51, v50, 0.5
	v_fma_f32 v50, v51, v50, 1.0
	v_mul_f32_e64 v50, v50, -v51
	s_or_saveexec_b64 s[10:11], s[10:11]
	v_mul_f32_e32 v46, 0x3fb8aa3b, v46
	v_exp_f32_e32 v46, v46
	s_xor_b64 exec, exec, s[10:11]
	v_fma_f32 v50, -v46, v46, 1.0
	s_or_b64 exec, exec, s[10:11]
	v_add_f32_e32 v42, v154, v42
	v_mul_f32_e32 v42, 0xbfb8aa3b, v42
	v_exp_f32_e32 v42, v42
	v_max_f32_e32 v50, v50, v50
	v_add_f32_e32 v47, v151, v47
	v_max_f32_e32 v50, 0, v50
	v_add_f32_e32 v42, 1.0, v42
	v_rcp_f32_e32 v42, v42
	v_mul_f32_e32 v47, 0xbfb8aa3b, v47
	v_sqrt_f32_e32 v50, v50
	v_exp_f32_e32 v47, v47
	v_mul_f32_e32 v0, v0, v42
	ds_write_b32 v169, v46 offset:51840
	v_mul_f32_e32 v42, v0, v50
	v_add_f32_e32 v0, 1.0, v47
	v_rcp_f32_e64 v47, -v0
	ds_read_b32 v0, v182 offset:18692
	ds_write_b32 v181, v42
	v_mul_f32_e32 v42, v160, v47
	v_add_f32_e32 v47, v42, v42
	v_cmp_ngt_f32_e32 vcc, s40, v47
	s_and_saveexec_b64 s[10:11], vcc
	s_xor_b64 s[10:11], exec, s[10:11]
	v_mov_b32_e32 v46, 0x3e2aaaab
	v_fmamk_f32 v46, v47, 0x3d2aaaab, v46
	v_fma_f32 v46, v47, v46, 0.5
	v_fma_f32 v46, v47, v46, 1.0
	v_mul_f32_e64 v46, v46, -v47
	s_or_saveexec_b64 s[10:11], s[10:11]
	v_mul_f32_e32 v42, 0x3fb8aa3b, v42
	v_exp_f32_e32 v42, v42
	s_xor_b64 exec, exec, s[10:11]
	v_fma_f32 v46, -v42, v42, 1.0
	s_or_b64 exec, exec, s[10:11]
	v_add_f32_e32 v43, v154, v43
	v_mul_f32_e32 v43, 0xbfb8aa3b, v43
	v_exp_f32_e32 v43, v43
	v_add_f32_e32 v47, v151, v48
	v_max_f32_e32 v46, v46, v46
	v_mul_f32_e32 v47, 0xbfb8aa3b, v47
	v_add_f32_e32 v43, 1.0, v43
	v_max_f32_e32 v46, 0, v46
	v_rcp_f32_e32 v43, v43
	v_exp_f32_e32 v47, v47
	v_sqrt_f32_e32 v46, v46
	ds_write_b32 v182, v42 offset:51972
	s_waitcnt lgkmcnt(0)
	v_mul_f32_e32 v0, v43, v0
	v_add_f32_e32 v42, 1.0, v47
	v_mul_f32_e32 v0, v0, v46
	v_rcp_f32_e64 v42, -v42
	ds_write_b32 v183, v0
	ds_read_b32 v0, v182 offset:18952
	v_mul_f32_e32 v42, v160, v42
	v_add_f32_e32 v46, v42, v42
	v_cmp_ngt_f32_e32 vcc, s40, v46
	s_and_saveexec_b64 s[10:11], vcc
	s_xor_b64 s[10:11], exec, s[10:11]
	v_mov_b32_e32 v43, 0x3e2aaaab
	v_fmamk_f32 v43, v46, 0x3d2aaaab, v43
	v_fma_f32 v43, v46, v43, 0.5
	v_fma_f32 v43, v46, v43, 1.0
	v_mul_f32_e64 v43, v43, -v46
	s_or_saveexec_b64 s[10:11], s[10:11]
	v_mul_f32_e32 v42, 0x3fb8aa3b, v42
	v_exp_f32_e32 v42, v42
	s_xor_b64 exec, exec, s[10:11]
	v_fma_f32 v43, -v42, v42, 1.0
	s_or_b64 exec, exec, s[10:11]
	v_add_f32_e32 v44, v154, v44
	v_mul_f32_e32 v44, 0xbfb8aa3b, v44
	v_exp_f32_e32 v44, v44
	v_add_f32_e32 v46, v151, v49
	v_max_f32_e32 v43, v43, v43
	v_mul_f32_e32 v46, 0xbfb8aa3b, v46
	v_add_f32_e32 v44, 1.0, v44
	v_max_f32_e32 v43, 0, v43
	v_rcp_f32_e32 v44, v44
	v_exp_f32_e32 v46, v46
	v_sqrt_f32_e32 v43, v43
	ds_write_b32 v182, v42 offset:52232
	s_waitcnt lgkmcnt(0)
	v_mul_f32_e32 v0, v44, v0
	v_add_f32_e32 v42, 1.0, v46
	v_mul_f32_e32 v0, v0, v43
	v_rcp_f32_e64 v42, -v42
	ds_write_b32 v184, v0
	ds_read_b32 v0, v182 offset:19212
	v_mul_f32_e32 v43, v160, v42
	v_add_f32_e32 v44, v43, v43
	v_cmp_ngt_f32_e32 vcc, s40, v44
	s_and_saveexec_b64 s[10:11], vcc
	s_xor_b64 s[10:11], exec, s[10:11]
	v_mov_b32_e32 v42, 0x3e2aaaab
	v_fmamk_f32 v42, v44, 0x3d2aaaab, v42
	v_fma_f32 v42, v44, v42, 0.5
	v_fma_f32 v42, v44, v42, 1.0
	v_mul_f32_e64 v42, v42, -v44
	s_or_saveexec_b64 s[10:11], s[10:11]
	v_mul_f32_e32 v43, 0x3fb8aa3b, v43
	v_exp_f32_e32 v43, v43
	s_xor_b64 exec, exec, s[10:11]
	v_fma_f32 v42, -v43, v43, 1.0
	s_or_b64 exec, exec, s[10:11]
	v_add_f32_e32 v44, v154, v45
	v_mul_f32_e32 v44, 0xbfb8aa3b, v44
	v_exp_f32_e32 v44, v44
	v_max_f32_e32 v42, v42, v42
	v_max_f32_e32 v42, 0, v42
	v_sqrt_f32_e32 v42, v42
	v_add_f32_e32 v44, 1.0, v44
	v_rcp_f32_e32 v44, v44
	ds_write_b32 v182, v43 offset:52492
	s_waitcnt lgkmcnt(0)
	v_mul_f32_e32 v0, v44, v0
	v_mul_f32_e32 v0, v0, v42
	ds_write_b32 v185, v0
	ds_read_b128 v[42:45], v186
	ds_read_b128 v[46:49], v186 offset:64
	ds_read_b128 v[50:53], v186 offset:9216
	s_waitcnt lgkmcnt(0)
	v_mfma_f32_16x16x32_bf16 v[42:45], v[38:41], v[42:45], 0
	v_mfma_f32_16x16x32_bf16 v[42:45], v[34:37], v[46:49], v[42:45]
	ds_read_b128 v[46:49], v186 offset:9280
	v_mfma_f32_16x16x32_bf16 v[38:41], v[38:41], v[50:53], 0
	s_nop 5
	v_add_f32_e32 v0, v156, v42
	v_mul_f32_e32 v0, 0xbfb8aa3b, v0
	v_exp_f32_e32 v0, v0
	s_nop 0
	v_add_f32_e32 v0, 1.0, v0
	v_rcp_f32_e64 v42, -v0
	ds_read_b32 v0, v169 offset:18624
	s_waitcnt lgkmcnt(0)
; DEVI float sigmoidf_(float x) { return __builtin_amdgcn_rcpf(1.f + __expf(-x)); }
; #define LBAR() do { asm volatile("s_waitcnt lgkmcnt(0)" ::: "memory"); __builtin_amdgcn_s_barrier(); asm volatile("" ::: "memory"); } while (0)
; DEVI void rnn_local_phase(const bf16_t* xr, const float* convw, const float* convb, const bf16_t* lruT, const float* ba, const float* bx, const float* lam,
;                           bf16_t* hloc, bf16_t* pcum, float* aggA, float* aggH, char* lds, int wv) {
;     ...
;             for (int cg = 0; cg < 4; ++cg) { const int ch = cg * 16 + l16;
;                 f32x4 ca = {0.f, 0.f, 0.f, 0.f}, cx = {0.f, 0.f, 0.f, 0.f};
;                 const bf16x8 wa0 = *(const bf16x8*)(WtL + ch * 72 + q4 * 8), wa1 = *(const bf16x8*)(WtL + ch * 72 + 32 + q4 * 8);
;                 const bf16x8 wx0 = *(const bf16x8*)(WtL + (64 + ch) * 72 + q4 * 8), wx1 = *(const bf16x8*)(WtL + (64 + ch) * 72 + 32 + q4 * 8);
;                 ca = __builtin_amdgcn_mfma_f32_16x16x32_bf16(a0, wa0, ca, 0, 0, 0); ca = __builtin_amdgcn_mfma_f32_16x16x32_bf16(a1, wa1, ca, 0, 0, 0);
;                 cx = __builtin_amdgcn_mfma_f32_16x16x32_bf16(a0, wx0, cx, 0, 0, 0); cx = __builtin_amdgcn_mfma_f32_16x16x32_bf16(a1, wx1, cx, 0, 0, 0);
; #pragma unroll
;                 for (int i = 0; i < 4; ++i) { const int tk = wave * 16 + q4 * 4 + i; const float xv = xcf[tk * 65 + ch];
;                     const float r = sigmoidf_(ca[i] + bav[cg]), ig = sigmoidf_(cx[i] + bxv[cg]), la = -r * sp8[cg], a = __expf(la);
;                     const float y2 = 2.f * la; const float om = y2 < -0.05f ? 1.f - a * a : -y2 * (1.f + y2 * (0.5f + y2 * (0.16666667f + y2 * 0.041666668f)));
;                     const float u = __builtin_amdgcn_sqrtf(fmaxf(om, 0.f)) * (ig * xv);
;                     aL[tk * 65 + ch] = a; uL[tk * 65 + ch] = u; } }
;         }
;         LBAR();
	v_mfma_f32_16x16x32_bf16 v[34:37], v[34:37], v[46:49], v[38:41]
	s_nop 2
	v_mul_f32_e32 v38, v161, v42
	v_add_f32_e32 v40, v38, v38
	v_cmp_ngt_f32_e32 vcc, s40, v40
	s_and_saveexec_b64 s[10:11], vcc
	s_xor_b64 s[10:11], exec, s[10:11]
	v_mov_b32_e32 v39, 0x3e2aaaab
	v_fmamk_f32 v39, v40, 0x3d2aaaab, v39
	v_fma_f32 v39, v40, v39, 0.5
	v_fma_f32 v39, v40, v39, 1.0
	v_mul_f32_e64 v39, v39, -v40
	s_or_saveexec_b64 s[10:11], s[10:11]
	v_mul_f32_e32 v38, 0x3fb8aa3b, v38
	v_exp_f32_e32 v38, v38
	s_xor_b64 exec, exec, s[10:11]
	v_fma_f32 v39, -v38, v38, 1.0
	s_or_b64 exec, exec, s[10:11]
	v_add_f32_e32 v34, v155, v34
	v_mul_f32_e32 v34, 0xbfb8aa3b, v34
	v_exp_f32_e32 v34, v34
	v_max_f32_e32 v39, v39, v39
	v_add_f32_e32 v40, v156, v43
	v_max_f32_e32 v39, 0, v39
	v_add_f32_e32 v34, 1.0, v34
	v_rcp_f32_e32 v34, v34
	v_mul_f32_e32 v40, 0xbfb8aa3b, v40
	v_sqrt_f32_e32 v39, v39
	v_exp_f32_e32 v40, v40
	v_mul_f32_e32 v0, v0, v34
	ds_write_b32 v169, v38 offset:51904
	v_mul_f32_e32 v34, v0, v39
	v_add_f32_e32 v0, 1.0, v40
	v_rcp_f32_e64 v39, -v0
	ds_read_b32 v0, v188 offset:18692
	ds_write_b32 v187, v34
	v_mul_f32_e32 v34, v161, v39
	v_add_f32_e32 v39, v34, v34
	v_cmp_ngt_f32_e32 vcc, s40, v39
	s_and_saveexec_b64 s[10:11], vcc
	s_xor_b64 s[10:11], exec, s[10:11]
	v_mov_b32_e32 v38, 0x3e2aaaab
	v_fmamk_f32 v38, v39, 0x3d2aaaab, v38
	v_fma_f32 v38, v39, v38, 0.5
	v_fma_f32 v38, v39, v38, 1.0
	v_mul_f32_e64 v38, v38, -v39
	s_or_saveexec_b64 s[10:11], s[10:11]
	v_mul_f32_e32 v34, 0x3fb8aa3b, v34
	v_exp_f32_e32 v34, v34
	s_xor_b64 exec, exec, s[10:11]
	v_fma_f32 v38, -v34, v34, 1.0
	s_or_b64 exec, exec, s[10:11]
	v_add_f32_e32 v35, v155, v35
	v_mul_f32_e32 v35, 0xbfb8aa3b, v35
	v_exp_f32_e32 v35, v35
	v_add_f32_e32 v39, v156, v44
	v_max_f32_e32 v38, v38, v38
	v_mul_f32_e32 v39, 0xbfb8aa3b, v39
	v_add_f32_e32 v35, 1.0, v35
	v_max_f32_e32 v38, 0, v38
	v_rcp_f32_e32 v35, v35
	v_exp_f32_e32 v39, v39
	v_sqrt_f32_e32 v38, v38
	ds_write_b32 v188, v34 offset:51972
	s_waitcnt lgkmcnt(0)
	v_mul_f32_e32 v0, v35, v0
	v_add_f32_e32 v34, 1.0, v39
	v_mul_f32_e32 v0, v0, v38
	v_rcp_f32_e64 v34, -v34
	ds_write_b32 v189, v0
	ds_read_b32 v0, v188 offset:18952
	v_mul_f32_e32 v34, v161, v34
	v_add_f32_e32 v38, v34, v34
	v_cmp_ngt_f32_e32 vcc, s40, v38
	s_and_saveexec_b64 s[10:11], vcc
	s_xor_b64 s[10:11], exec, s[10:11]
	v_mov_b32_e32 v35, 0x3e2aaaab
	v_fmamk_f32 v35, v38, 0x3d2aaaab, v35
	v_fma_f32 v35, v38, v35, 0.5
	v_fma_f32 v35, v38, v35, 1.0
	v_mul_f32_e64 v35, v35, -v38
	s_or_saveexec_b64 s[10:11], s[10:11]
	v_mul_f32_e32 v34, 0x3fb8aa3b, v34
	v_exp_f32_e32 v34, v34
	s_xor_b64 exec, exec, s[10:11]
	v_fma_f32 v35, -v34, v34, 1.0
	s_or_b64 exec, exec, s[10:11]
	v_add_f32_e32 v36, v155, v36
	v_mul_f32_e32 v36, 0xbfb8aa3b, v36
	v_exp_f32_e32 v36, v36
	v_add_f32_e32 v38, v156, v45
	v_max_f32_e32 v35, v35, v35
	v_mul_f32_e32 v38, 0xbfb8aa3b, v38
	v_add_f32_e32 v36, 1.0, v36
	v_max_f32_e32 v35, 0, v35
	v_rcp_f32_e32 v36, v36
	v_exp_f32_e32 v38, v38
	v_sqrt_f32_e32 v35, v35
	ds_write_b32 v188, v34 offset:52232
	s_waitcnt lgkmcnt(0)
	v_mul_f32_e32 v0, v36, v0
	v_add_f32_e32 v34, 1.0, v38
	v_mul_f32_e32 v0, v0, v35
	v_rcp_f32_e64 v35, -v34
	ds_write_b32 v190, v0
	ds_read_b32 v34, v188 offset:19212
	v_mul_f32_e32 v0, v161, v35
	v_add_f32_e32 v35, v0, v0
	v_cmp_ngt_f32_e32 vcc, s40, v35
	s_and_saveexec_b64 s[10:11], vcc
	s_xor_b64 s[10:11], exec, s[10:11]
	v_mov_b32_e32 v36, 0x3e2aaaab
	v_fmamk_f32 v36, v35, 0x3d2aaaab, v36
	v_fma_f32 v36, v35, v36, 0.5
	v_fma_f32 v36, v35, v36, 1.0
	v_mul_f32_e64 v36, v36, -v35
	s_or_saveexec_b64 s[10:11], s[10:11]
	v_mul_f32_e32 v0, 0x3fb8aa3b, v0
	v_exp_f32_e32 v35, v0
	s_xor_b64 exec, exec, s[10:11]
	v_fma_f32 v36, -v35, v35, 1.0
	s_or_b64 exec, exec, s[10:11]
	v_add_f32_e32 v0, v155, v37
	v_mul_f32_e32 v0, 0xbfb8aa3b, v0
	v_exp_f32_e32 v37, v0
	v_max_f32_e32 v38, v36, v36
	v_max_f32_e32 v38, 0, v38
	v_sqrt_f32_e32 v38, v38
	v_add_f32_e32 v37, 1.0, v37
	v_rcp_f32_e32 v37, v37
	v_add_u32_e32 v39, 0xcc00, v192
	v_mov_b32_e32 v0, 1.0
	v_mov_b32_e32 v36, 0
	s_waitcnt lgkmcnt(0)
	v_mul_f32_e32 v34, v37, v34
	v_mul_f32_e32 v34, v34, v38
	ds_write_b32 v188, v35 offset:52492
	ds_write_b32 v191, v34
	s_waitcnt lgkmcnt(0)
	s_barrier
; #define LBAR() do { asm volatile("s_waitcnt lgkmcnt(0)" ::: "memory"); __builtin_amdgcn_s_barrier(); asm volatile("" ::: "memory"); } while (0)
; DEVI void rnn_local_phase(const bf16_t* xr, const float* convw, const float* convb, const bf16_t* lruT, const float* ba, const float* bx, const float* lam,
;                           bf16_t* hloc, bf16_t* pcum, float* aggA, float* aggH, char* lds, int wv) {
;     ...
;         {
;             float h = 0.f, P = 1.f;
; #pragma unroll
;             for (int i = 0; i < 16; ++i) { const int o = (wave * 16 + i) * 65 + lane; const float a = aL[o], u = uL[o]; h = a * h + u; P *= a; uL[o] = h; aL[o] = P; }
;             segA[wave * 64 + lane] = P; segH[wave * 64 + lane] = h;
;         }
;         LBAR();
;         {
;             float Ain = 1.f, Hin = 0.f;
;             for (int s = 0; s < wave; ++s) { const float As = segA[s * 64 + lane], Hs = segH[s * 64 + lane]; Hin = As * Hin + Hs; Ain *= As; }
	v_add_u32_e32 v215, 0x14c00, v192
	ds_read_b32 v212, v192 offset:51712
	ds_read_b32 v213, v215
	ds_read_b32 v222, v192 offset:51972
	ds_read_b32 v223, v215 offset:260
	ds_read_b32 v224, v192 offset:52232
	ds_read_b32 v225, v215 offset:520
	ds_read_b32 v226, v192 offset:52492
	ds_read_b32 v227, v215 offset:780
	ds_read_b32 v228, v192 offset:52752
	ds_read_b32 v229, v215 offset:1040
	ds_read_b32 v230, v192 offset:53012
	ds_read_b32 v231, v215 offset:1300
	ds_read_b32 v232, v192 offset:53272
	ds_read_b32 v233, v215 offset:1560
	ds_read_b32 v234, v192 offset:53532
	ds_read_b32 v235, v215 offset:1820
	ds_read_b32 v236, v192 offset:53792
	ds_read_b32 v237, v215 offset:2080
	ds_read_b32 v238, v192 offset:54052
	ds_read_b32 v239, v215 offset:2340
	ds_read_b32 v240, v192 offset:54312
	ds_read_b32 v241, v215 offset:2600
	ds_read_b32 v242, v192 offset:54572
	ds_read_b32 v243, v215 offset:2860
	ds_read_b32 v244, v192 offset:54832
	ds_read_b32 v245, v215 offset:3120
	ds_read_b32 v246, v192 offset:55092
	ds_read_b32 v247, v215 offset:3380
	ds_read_b32 v248, v192 offset:55352
	ds_read_b32 v249, v215 offset:3640
	ds_read_b32 v250, v192 offset:55612
	ds_read_b32 v251, v215 offset:3900
	s_andn2_b64 vcc, exec, s[4:5]
	s_waitcnt lgkmcnt(15)
	v_fmac_f32_e32 v213, 0, v212
	v_fmac_f32_e32 v223, v213, v222
	v_mul_f32_e32 v222, v212, v222
	v_fmac_f32_e32 v225, v223, v224
	v_mul_f32_e32 v224, v222, v224
	v_fmac_f32_e32 v227, v225, v226
	v_mul_f32_e32 v226, v224, v226
	v_fmac_f32_e32 v229, v227, v228
	v_mul_f32_e32 v228, v226, v228
	v_fmac_f32_e32 v231, v229, v230
	v_mul_f32_e32 v230, v228, v230
	v_fmac_f32_e32 v233, v231, v232
	v_mul_f32_e32 v232, v230, v232
	v_fmac_f32_e32 v235, v233, v234
	v_mul_f32_e32 v234, v232, v234
	s_waitcnt lgkmcnt(14)
	v_fmac_f32_e32 v237, v235, v236
	v_mul_f32_e32 v236, v234, v236
	s_waitcnt lgkmcnt(12)
	v_fmac_f32_e32 v239, v237, v238
	v_mul_f32_e32 v238, v236, v238
	s_waitcnt lgkmcnt(10)
	v_fmac_f32_e32 v241, v239, v240
	v_mul_f32_e32 v240, v238, v240
	s_waitcnt lgkmcnt(8)
	v_fmac_f32_e32 v243, v241, v242
	v_mul_f32_e32 v242, v240, v242
	s_waitcnt lgkmcnt(6)
	v_fmac_f32_e32 v245, v243, v244
	v_mul_f32_e32 v244, v242, v244
	s_waitcnt lgkmcnt(4)
	v_fmac_f32_e32 v247, v245, v246
	v_mul_f32_e32 v246, v244, v246
	s_waitcnt lgkmcnt(2)
	v_fmac_f32_e32 v249, v247, v248
	v_mul_f32_e32 v248, v246, v248
	s_waitcnt lgkmcnt(0)
	v_fmac_f32_e32 v251, v249, v250
	v_mul_f32_e32 v250, v248, v250
	ds_write_b32 v215, v213
	ds_write_b32 v215, v223 offset:260
	ds_write_b32 v192, v222 offset:51972
	ds_write_b32 v215, v225 offset:520
	ds_write_b32 v192, v224 offset:52232
	ds_write_b32 v215, v227 offset:780
	ds_write_b32 v192, v226 offset:52492
	ds_write_b32 v215, v229 offset:1040
	ds_write_b32 v192, v228 offset:52752
	ds_write_b32 v215, v231 offset:1300
	ds_write_b32 v192, v230 offset:53012
	ds_write_b32 v215, v233 offset:1560
	ds_write_b32 v192, v232 offset:53272
	ds_write_b32 v215, v235 offset:1820
	ds_write_b32 v192, v234 offset:53532
	ds_write_b32 v215, v237 offset:2080
	ds_write_b32 v192, v236 offset:53792
	ds_write_b32 v215, v239 offset:2340
	ds_write_b32 v192, v238 offset:54052
	ds_write_b32 v215, v241 offset:2600
	ds_write_b32 v192, v240 offset:54312
	ds_write_b32 v215, v243 offset:2860
	ds_write_b32 v192, v242 offset:54572
	ds_write_b32 v215, v245 offset:3120
	ds_write_b32 v192, v244 offset:54832
	ds_write_b32 v215, v247 offset:3380
	ds_write_b32 v192, v246 offset:55092
	ds_write_b32 v215, v249 offset:3640
	ds_write_b32 v192, v248 offset:55352
	ds_write_b32 v215, v251 offset:3900
	ds_write_b32 v192, v250 offset:55612
	ds_write_b32 v166, v250
	ds_write_b32 v167, v251
	s_waitcnt lgkmcnt(0)
	s_barrier
	s_cbranch_vccnz .LBB0_190
	v_mov_b32_e32 v0, 1.0
	v_mov_b32_e32 v36, 0
	v_mov_b32_e32 v34, v219
	s_mov_b32 s10, s46
